# v57 + 128-row GEMM prologue: K-tile 1 LDS-DMA loads issued before the wait for K-tile 0 (counted vmcnt(6))
# baseline (speedup 1.0000x reference)
.LBB0_36:
	s_ashr_i32 s20, s48, 31
	v_and_b32_e32 v0, 15, v4
	v_lshrrev_b32_e32 v1, 4, v4
	s_lshr_b32 s20, s20, 26
	v_and_b32_e32 v7, 7, v4
	s_add_i32 s20, s48, s20
	v_lshlrev_b32_e32 v5, 7, v0
	v_bitop3_b32 v1, v1, v7, 3 bitop3:0x6c
	s_ashr_i32 s79, s20, 6
	v_lshl_or_b32 v6, s40, 13, v5
	v_lshlrev_b32_e32 v1, 4, v1
	s_add_i32 s20, s68, 0x80
	s_and_b32 s43, s38, 3
	s_lshl_b32 s81, s87, 8
	v_or_b32_e32 v160, v6, v1
	v_bitop3_b32 v161, v6, 64, v1 bitop3:0x36
	v_lshl_add_u64 v[6:7], v[132:133], 0, s[20:21]
	s_add_i32 m0, s78, 0xc000
	s_add_i32 s38, s20, s77
	s_mov_b32 s39, s21
	global_load_lds_dwordx4 v[6:7], off
	v_lshl_add_u64 v[6:7], v[132:133], 0, s[38:39]
	s_add_i32 m0, s78, 0xe000
	s_add_i32 s20, s20, s81
	global_load_lds_dwordx4 v[6:7], off
	s_add_i32 m0, s78, 0x10000
	v_lshl_add_u64 v[6:7], v[132:133], 0, s[20:21]
	s_add_i32 s20, s20, s77
	global_load_lds_dwordx4 v[6:7], off
	v_lshl_add_u64 v[6:7], v[132:133], 0, s[20:21]
	s_add_i32 m0, s78, 0x12000
	s_add_i32 s20, s42, 0x80
	global_load_lds_dwordx4 v[6:7], off
	s_add_i32 m0, s78, 0x14000
	v_lshl_add_u64 v[6:7], v[134:135], 0, s[20:21]
	s_add_i32 s20, s20, s76
	global_load_lds_dwordx4 v[6:7], off
	v_lshl_add_u64 v[6:7], v[134:135], 0, s[20:21]
	s_add_i32 m0, s78, 0x16000
	s_cmp_gt_i32 s48, 63
	global_load_lds_dwordx4 v[6:7], off
	s_waitcnt vmcnt(6)
	s_barrier
	s_cselect_b64 s[48:49], -1, 0
	s_cmpk_lt_u32 s9, 0x100
	v_lshl_or_b32 v5, s43, 12, v5
	s_cselect_b64 s[50:51], -1, 0
	s_lshl_b32 s9, s40, 2
	v_or_b32_e32 v162, v5, v1
	v_bitop3_b32 v163, v5, 64, v1 bitop3:0x36
	s_or_b32 s9, s9, s43
	v_and_b32_e32 v5, 63, v4
	v_lshl_or_b32 v165, s40, 6, v0
	v_lshl_or_b32 v136, s9, 6, v5
	s_lshl_b32 s62, s40, 10
	s_movk_i32 s40, 0x80
	v_cmp_gt_i32_e64 s[40:41], s40, v136
	v_cmp_eq_u32_e32 vcc, 0, v5
	s_lshl_b32 s20, s43, 6
	s_and_b64 s[52:53], vcc, s[40:41]
	s_cmp_eq_u32 s9, 0
	v_ashrrev_i32_e32 v137, 31, v136
	s_cselect_b64 s[54:55], -1, 0
	s_mov_b64 s[56:57], 0x2000
	s_add_u32 s83, s10, 0x100000
	v_readlane_b32 s60, v254, 57
	v_lshl_add_u64 v[138:139], v[136:137], 0, s[56:57]
	s_addc_u32 s84, s11, 0
	s_lshl_b32 s56, s60, 12
	s_ashr_i32 s57, s56, 31
	s_lshl_b64 s[56:57], s[56:57], 2
	s_add_u32 s9, s10, s56
	s_addc_u32 s56, s11, s57
	s_add_u32 s85, s9, 0xa000
	v_bfe_u32 v2, v4, 4, 2
	s_addc_u32 s86, s56, 0
	s_lshl_b32 s9, s43, 7
	v_lshlrev_b32_e32 v1, 2, v2
	v_and_b32_e32 v4, 16, v4
	s_add_u32 s56, s10, s9
	v_lshlrev_b32_e32 v6, 2, v5
	v_cmp_eq_u32_e64 s[38:39], 0, v2
	v_add_u32_e32 v5, 12, v1
	v_cmp_eq_u32_e32 vcc, 0, v4
	v_lshlrev_b32_e32 v2, 5, v2
	s_addc_u32 s57, s11, 0
	v_lshl_or_b32 v164, s43, 5, v1
	v_cndmask_b32_e32 v1, v5, v1, vcc
	v_lshl_add_u64 v[4:5], s[56:57], 0, v[2:3]
	s_mov_b64 s[56:57], 0xf000000
	s_cmp_lt_i32 s60, 1
	v_lshl_add_u64 v[140:141], v[4:5], 0, s[56:57]
	s_cselect_b64 s[56:57], -1, 0
	s_cmp_gt_i32 s60, 0
	s_cselect_b64 s[58:59], -1, 0
	s_lshl_b32 s9, s60, 1
	s_or_b32 s60, s9, 1
	s_ashr_i32 s61, s60, 31
	s_lshl_b64 s[60:61], s[60:61], 12
	s_waitcnt lgkmcnt(0)
	s_add_u32 s6, s6, s60
	s_addc_u32 s7, s7, s61
	s_add_u32 s60, s10, 0x180000
	s_addc_u32 s61, s11, 0
	s_add_i32 s62, s62, 0
	s_lshl_b32 s43, s43, 2
	s_add_i32 s43, s62, s43
	s_mov_b64 s[62:63], 0x8c00000
	v_lshl_add_u64 v[142:143], v[4:5], 0, s[62:63]
	s_add_i32 s62, s9, 2
	s_ashr_i32 s63, s62, 31
	s_add_i32 s43, s43, 0x26000
	s_lshl_b64 s[62:63], s[62:63], 12
	s_add_u32 s62, s4, s62
	s_addc_u32 s63, s5, s63
	s_add_u32 s4, s10, s20
	s_addc_u32 s5, s11, 0
	v_lshlrev_b32_e32 v2, 1, v1
	v_or_b32_e32 v169, 16, v165
	v_or_b32_e32 v170, 32, v165
	v_or_b32_e32 v171, 48, v165
	v_lshl_add_u32 v172, v0, 4, s43
	v_readlane_b32 s43, v254, 43
	v_lshl_add_u64 v[4:5], s[4:5], 0, v[2:3]
	s_mov_b64 s[4:5], 0x5000000
	v_xor_b32_e32 v166, 64, v6
	v_xor_b32_e32 v167, 0x80, v6
	s_mov_b32 s82, 0
	v_lshlrev_b32_e32 v168, 4, v136
	v_lshl_add_u32 v173, v136, 2, s43
	v_lshl_add_u32 v174, v165, 2, s43
	v_lshl_add_u32 v175, v169, 2, s43
	v_lshl_add_u32 v176, v170, 2, s43
	v_lshl_add_u32 v177, v171, 2, s43
	v_lshl_add_u64 v[144:145], v[4:5], 0, s[4:5]
	s_mulk_i32 s87, 0x180
	s_mov_b32 s88, 0
	s_barrier
	s_branch .LBB0_39

.LBB0_404:
	s_ashr_i32 s20, s50, 31
	v_and_b32_e32 v0, 15, v4
	v_lshrrev_b32_e32 v1, 4, v4
	s_lshr_b32 s20, s20, 26
	v_and_b32_e32 v7, 7, v4
	s_add_i32 s20, s50, s20
	v_lshlrev_b32_e32 v5, 7, v0
	v_bitop3_b32 v1, v1, v7, 3 bitop3:0x6c
	s_ashr_i32 s84, s20, 6
	v_lshl_or_b32 v6, s40, 13, v5
	v_lshlrev_b32_e32 v1, 4, v1
	s_add_i32 s20, s72, 0x80
	s_and_b32 s43, s38, 3
	s_lshl_b32 s85, s91, 8
	v_or_b32_e32 v190, v6, v1
	v_bitop3_b32 v191, v6, 64, v1 bitop3:0x36
	v_lshl_add_u64 v[6:7], v[164:165], 0, s[20:21]
	s_add_i32 m0, s83, 0xc000
	s_add_i32 s38, s20, s82
	s_mov_b32 s39, s21
	global_load_lds_dwordx4 v[6:7], off
	v_lshl_add_u64 v[6:7], v[164:165], 0, s[38:39]
	s_add_i32 m0, s83, 0xe000
	s_add_i32 s20, s20, s85
	global_load_lds_dwordx4 v[6:7], off
	s_add_i32 m0, s83, 0x10000
	v_lshl_add_u64 v[6:7], v[164:165], 0, s[20:21]
	s_add_i32 s20, s20, s82
	global_load_lds_dwordx4 v[6:7], off
	v_lshl_add_u64 v[6:7], v[164:165], 0, s[20:21]
	s_add_i32 m0, s83, 0x12000
	s_add_i32 s20, s42, 0x80
	global_load_lds_dwordx4 v[6:7], off
	s_add_i32 m0, s83, 0x14000
	v_lshl_add_u64 v[6:7], v[166:167], 0, s[20:21]
	s_add_i32 s20, s20, s81
	global_load_lds_dwordx4 v[6:7], off
	v_lshl_add_u64 v[6:7], v[166:167], 0, s[20:21]
	s_add_i32 m0, s83, 0x16000
	s_cmp_gt_i32 s50, 63
	global_load_lds_dwordx4 v[6:7], off
	s_waitcnt vmcnt(6)
	s_barrier
	s_cselect_b64 s[50:51], -1, 0
	s_cmpk_lt_u32 s9, 0x100
	v_lshl_or_b32 v5, s43, 12, v5
	s_cselect_b64 s[52:53], -1, 0
	s_lshl_b32 s9, s40, 2
	v_or_b32_e32 v192, v5, v1
	v_bitop3_b32 v193, v5, 64, v1 bitop3:0x36
	s_or_b32 s9, s9, s43
	v_and_b32_e32 v5, 63, v4
	v_lshl_or_b32 v195, s40, 6, v0
	v_lshl_or_b32 v168, s9, 6, v5
	s_lshl_b32 s68, s40, 10
	s_movk_i32 s40, 0x80
	v_cmp_gt_i32_e64 s[40:41], s40, v168
	v_cmp_eq_u32_e32 vcc, 0, v5
	s_lshl_b32 s20, s43, 6
	s_and_b64 s[54:55], vcc, s[40:41]
	s_cmp_eq_u32 s9, 0
	v_ashrrev_i32_e32 v169, 31, v168
	s_cselect_b64 s[56:57], -1, 0
	s_mov_b64 s[58:59], 0x2000
	s_add_u32 s87, s10, 0x100000
	v_readlane_b32 s64, v254, 57
	v_lshl_add_u64 v[170:171], v[168:169], 0, s[58:59]
	s_addc_u32 s88, s11, 0
	s_lshl_b32 s58, s64, 12
	s_ashr_i32 s59, s58, 31
	s_lshl_b64 s[58:59], s[58:59], 2
	s_add_u32 s9, s10, s58
	s_addc_u32 s58, s11, s59
	s_add_u32 s89, s9, 0x8000
	s_addc_u32 s90, s58, 0
	v_readlane_b32 s9, v254, 60
	s_cmp_gt_u32 s9, 7
	v_bfe_u32 v2, v4, 4, 2
	s_cselect_b64 s[58:59], -1, 0
	s_lshl_b32 s9, s43, 7
	v_lshlrev_b32_e32 v1, 2, v2
	v_and_b32_e32 v4, 16, v4
	s_add_u32 s60, s10, s9
	v_lshlrev_b32_e32 v6, 2, v5
	v_cmp_eq_u32_e64 s[38:39], 0, v2
	v_add_u32_e32 v5, 12, v1
	v_cmp_eq_u32_e32 vcc, 0, v4
	v_lshlrev_b32_e32 v2, 5, v2
	s_addc_u32 s61, s11, 0
	v_lshl_or_b32 v194, s43, 5, v1
	v_cndmask_b32_e32 v1, v5, v1, vcc
	v_lshl_add_u64 v[4:5], s[60:61], 0, v[2:3]
	s_mov_b64 s[60:61], 0x8c00000
	s_cmp_lt_i32 s64, 2
	v_lshl_add_u64 v[172:173], v[4:5], 0, s[60:61]
	s_cselect_b64 s[60:61], -1, 0
	s_cmp_gt_i32 s64, 1
	s_cselect_b64 s[62:63], -1, 0
	s_lshl_b32 s66, s64, 1
	s_ashr_i32 s67, s66, 31
	s_lshl_b64 s[64:65], s[66:67], 12
	s_waitcnt lgkmcnt(0)
	s_add_u32 s6, s6, s64
	s_addc_u32 s7, s7, s65
	s_add_u32 s64, s10, 0x180000
	s_addc_u32 s65, s11, 0
	s_add_i32 s9, s68, 0
	s_lshl_b32 s43, s43, 2
	s_or_b32 s66, s66, 1
	s_add_i32 s9, s9, s43
	s_ashr_i32 s67, s66, 31
	s_add_i32 s9, s9, 0x26000
	s_lshl_b64 s[66:67], s[66:67], 12
	s_add_u32 s66, s4, s66
	s_addc_u32 s67, s5, s67
	s_add_u32 s4, s10, s20
	s_mov_b64 s[68:69], 0xf000000
	s_addc_u32 s5, s11, 0
	v_lshlrev_b32_e32 v2, 1, v1
	v_or_b32_e32 v223, 16, v195
	v_or_b32_e32 v224, 32, v195
	v_or_b32_e32 v225, 48, v195
	v_lshl_add_u32 v226, v0, 4, s9
	v_readlane_b32 s9, v254, 43
	v_lshl_add_u64 v[174:175], v[4:5], 0, s[68:69]
	v_lshl_add_u64 v[4:5], s[4:5], 0, v[2:3]
	s_mov_b64 s[4:5], 0x5000000
	v_xor_b32_e32 v220, 64, v6
	v_xor_b32_e32 v221, 0x80, v6
	s_mov_b32 s86, 0
	v_lshlrev_b32_e32 v222, 4, v168
	v_lshl_add_u32 v227, v168, 2, s9
	v_lshl_add_u32 v228, v195, 2, s9
	v_lshl_add_u32 v229, v223, 2, s9
	v_lshl_add_u32 v230, v224, 2, s9
	v_lshl_add_u32 v231, v225, 2, s9
	v_lshl_add_u64 v[176:177], v[4:5], 0, s[4:5]
	s_mulk_i32 s91, 0x180
	s_mov_b32 s92, 0
	s_barrier
	s_branch .LBB0_407

.LBB0_552:
	s_add_u32 s44, s10, 0xb800000
	s_addc_u32 s45, s11, 0
	s_add_u32 s6, s10, 0xf000000
	s_addc_u32 s7, s11, 0
	s_ashr_i32 s20, s42, 31
	v_and_b32_e32 v0, 15, v4
	v_lshrrev_b32_e32 v1, 4, v4
	s_lshr_b32 s20, s20, 26
	v_and_b32_e32 v7, 7, v4
	s_add_i32 s20, s42, s20
	v_lshlrev_b32_e32 v2, 7, v0
	v_bitop3_b32 v1, v1, v7, 3 bitop3:0x6c
	s_ashr_i32 s54, s20, 6
	v_lshl_or_b32 v6, s39, 13, v2
	v_lshlrev_b32_e32 v1, 4, v1
	s_add_i32 s20, s38, 0x80
	s_lshl_b32 s55, s62, 8
	v_or_b32_e32 v131, v6, v1
	v_bitop3_b32 v138, v6, 64, v1 bitop3:0x36
	v_lshl_add_u64 v[6:7], v[126:127], 0, s[20:21]
	s_add_i32 m0, s53, 0xc000
	s_add_i32 s46, s20, s52
	s_mov_b32 s47, s21
	global_load_lds_dwordx4 v[6:7], off
	v_lshl_add_u64 v[6:7], v[126:127], 0, s[46:47]
	s_add_i32 m0, s53, 0xe000
	s_add_i32 s20, s20, s55
	global_load_lds_dwordx4 v[6:7], off
	s_add_i32 m0, s53, 0x10000
	v_lshl_add_u64 v[6:7], v[126:127], 0, s[20:21]
	s_add_i32 s20, s20, s52
	global_load_lds_dwordx4 v[6:7], off
	v_lshl_add_u64 v[6:7], v[126:127], 0, s[20:21]
	s_add_i32 m0, s53, 0x12000
	s_add_i32 s20, s40, 0x80
	global_load_lds_dwordx4 v[6:7], off
	s_add_i32 m0, s53, 0x14000
	v_lshl_add_u64 v[6:7], v[128:129], 0, s[20:21]
	s_add_i32 s20, s20, s17
	s_and_b32 s41, s43, 3
	global_load_lds_dwordx4 v[6:7], off
	v_lshl_add_u64 v[6:7], v[128:129], 0, s[20:21]
	s_lshl_b32 s20, s8, 7
	s_lshl_b32 s39, s39, 6
	v_lshl_or_b32 v2, s41, 12, v2
	s_add_i32 s20, s20, s39
	v_or_b32_e32 v139, v2, v1
	v_bitop3_b32 v140, v2, 64, v1 bitop3:0x36
	v_or_b32_e32 v1, s20, v0
	s_lshl_b32 s20, s57, 8
	s_lshl_b32 s43, s41, 6
	v_bfe_u32 v5, v4, 4, 2
	s_or_b32 s20, s20, s43
	s_add_i32 m0, s53, 0x16000
	v_lshl_or_b32 v2, v5, 4, s20
	s_movk_i32 s20, 0xc00
	global_load_lds_dwordx4 v[6:7], off
	s_waitcnt vmcnt(6)
	s_barrier
	v_mad_u64_u32 v[38:39], s[46:47], v1, s20, v[2:3]
	v_add_u32_e32 v1, 0xc000, v38
	global_load_dwordx4 v[6:9], v38, s[44:45]
	global_load_dwordx4 v[10:13], v38, s[44:45] offset:1024
	global_load_dwordx4 v[14:17], v38, s[44:45] offset:2048
	global_load_dwordx4 v[18:21], v1, s[44:45]
	global_load_dwordx4 v[22:25], v1, s[44:45] offset:1024
	global_load_dwordx4 v[26:29], v1, s[44:45] offset:2048
	v_add_u32_e32 v1, 0x18000, v38
	global_load_dwordx4 v[30:33], v1, s[44:45]
	global_load_dwordx4 v[34:37], v1, s[44:45] offset:1024
	v_add_u32_e32 v2, 0x24000, v38
	global_load_dwordx4 v[38:41], v1, s[44:45] offset:2048
	global_load_dwordx4 v[42:45], v2, s[44:45]
	global_load_dwordx4 v[46:49], v2, s[44:45] offset:1024
	global_load_dwordx4 v[50:53], v2, s[44:45] offset:2048
	s_cmp_gt_i32 s42, 63
	s_cselect_b64 s[44:45], -1, 0
	s_cmpk_lt_u32 s9, 0x100
	s_cselect_b64 s[46:47], -1, 0
	s_ashr_i32 s20, s36, 3
	s_and_b32 s20, s20, -4
	v_or_b32_e32 v0, s39, v0
	s_lshl_b32 s56, s41, 5
	s_and_b32 s9, s36, 7
	s_add_i32 s39, s20, 28
	s_cmp_lt_u32 s9, 4
	s_cselect_b32 s20, s20, s39
	s_ashr_i32 s39, s16, 31
	s_lshr_b32 s39, s39, 29
	s_add_i32 s39, s16, s39
	s_and_b32 s41, s39, -8
	s_sub_i32 s41, s16, s41
	s_add_i32 s20, s20, s9
	s_bfe_u32 s9, s36, 0x20003
	s_lshl_b32 s42, s41, 5
	s_ashr_i32 s39, s39, 3
	s_cmp_lt_i32 s41, 0
	s_mul_i32 s41, s41, 33
	s_cselect_b32 s41, s41, s42
	s_add_i32 s39, s41, s39
	s_ashr_i32 s41, s39, 31
	s_lshr_b32 s41, s41, 27
	s_add_i32 s41, s39, s41
	s_ashr_i32 s42, s41, 5
	s_and_b32 s41, s41, 0xffe0
	s_sub_i32 s39, s39, s41
	s_bfe_i32 s41, s39, 0x80000
	s_bfe_u32 s41, s41, 0x3000c
	s_add_i32 s41, s39, s41
	s_bfe_i32 s43, s41, 0x80000
	s_and_b32 s41, s41, 0xf8
	s_sub_i32 s39, s39, s41
	s_lshl_b32 s42, s42, 3
	s_sext_i32_i16 s43, s43
	s_sext_i32_i8 s39, s39
	s_add_i32 s39, s42, s39
	s_ashr_i32 s41, s43, 3
	v_readlane_b32 s42, v254, 58
	v_and_b32_e32 v1, 16, v4
	v_lshlrev_b32_e32 v2, 2, v5
	v_readlane_b32 s43, v254, 59
	v_add_u32_e32 v4, 12, v2
	v_cmp_eq_u32_e32 vcc, 0, v1
	s_and_b64 s[42:43], s[42:43], exec
	s_cselect_b32 s59, s41, s9
	v_cndmask_b32_e32 v130, v4, v2, vcc
	v_mov_b32_e32 v4, v3
	v_mov_b32_e32 v5, v3
	s_cselect_b32 s58, s39, s20
	s_lshl_b32 s9, s59, 18
	v_mov_b32_e32 v2, v3
	v_mov_b64_e32 v[124:125], v[4:5]
	v_mov_b64_e32 v[56:57], v[4:5]
	v_mov_b64_e32 v[60:61], v[4:5]
	v_mov_b64_e32 v[64:65], v[4:5]
	v_mov_b64_e32 v[68:69], v[4:5]
	v_mov_b64_e32 v[72:73], v[4:5]
	v_mov_b64_e32 v[76:77], v[4:5]
	v_mov_b64_e32 v[80:81], v[4:5]
	v_mov_b64_e32 v[84:85], v[4:5]
	v_mov_b64_e32 v[88:89], v[4:5]
	v_mov_b64_e32 v[92:93], v[4:5]
	v_mov_b64_e32 v[96:97], v[4:5]
	v_mov_b64_e32 v[100:101], v[4:5]
	v_mov_b64_e32 v[104:105], v[4:5]
	v_mov_b64_e32 v[108:109], v[4:5]
	v_mov_b64_e32 v[112:113], v[4:5]
	s_mov_b32 s68, 0
	v_lshlrev_b32_e32 v141, 10, v0
	s_lshl_b32 s60, s58, 19
	s_add_i32 s61, s61, s9
	s_mulk_i32 s62, 0x180
	v_mov_b64_e32 v[122:123], v[2:3]
	v_mov_b64_e32 v[54:55], v[2:3]
	v_mov_b64_e32 v[58:59], v[2:3]
	v_mov_b64_e32 v[62:63], v[2:3]
	v_mov_b64_e32 v[66:67], v[2:3]
	v_mov_b64_e32 v[70:71], v[2:3]
	v_mov_b64_e32 v[74:75], v[2:3]
	v_mov_b64_e32 v[78:79], v[2:3]
	v_mov_b64_e32 v[82:83], v[2:3]
	v_mov_b64_e32 v[86:87], v[2:3]
	v_mov_b64_e32 v[90:91], v[2:3]
	v_mov_b64_e32 v[94:95], v[2:3]
	v_mov_b64_e32 v[98:99], v[2:3]
	v_mov_b64_e32 v[102:103], v[2:3]
	v_mov_b64_e32 v[106:107], v[2:3]
	v_mov_b64_e32 v[110:111], v[2:3]
	s_mov_b32 s63, 0
	s_mov_b32 s69, 0
	s_barrier
	s_waitcnt vmcnt(0)
	s_branch .LBB0_555
